# hyena: gate loads batched and hoisted before the e-loop tail (sample + prompt), prompt u-tile loads paired, prompt e-loop unrolled and software-pipelined
# speedup vs baseline: 1.0076x; 1.0058x over previous
.LBB0_477:
	s_or_b64 exec, exec, s[0:1]
	s_waitcnt lgkmcnt(0)
	s_barrier
	ds_read_b128 v[0:3], v112 offset:25216
	ds_read_b128 v[4:7], v112 offset:25232
	ds_read_b128 v[8:11], v112 offset:25248
	ds_read_b128 v[12:15], v112 offset:25264
	s_mov_b32 s0, 0x358637bd
	s_waitcnt lgkmcnt(3)
	v_mov_b32_e32 v74, v0
	s_mov_b32 s63, s96
	s_waitcnt lgkmcnt(1)
	v_mov_b32_e32 v75, v8
	v_pk_add_f32 v[74:75], v[74:75], 0 op_sel_hi:[1,0]
	v_mov_b32_e32 v8, v1
	v_pk_add_f32 v[0:1], v[74:75], v[8:9]
	v_mov_b32_e32 v8, v2
	v_mov_b32_e32 v9, v10
	v_pk_add_f32 v[0:1], v[0:1], v[8:9]
	v_mov_b32_e32 v10, v3
	v_pk_add_f32 v[0:1], v[0:1], v[10:11]
	v_mov_b32_e32 v2, v4
	s_waitcnt lgkmcnt(0)
	v_mov_b32_e32 v3, v12
	v_pk_add_f32 v[0:1], v[0:1], v[2:3]
	v_mov_b32_e32 v12, v5
	v_pk_add_f32 v[0:1], v[0:1], v[12:13]
	v_mov_b32_e32 v2, v6
	v_mov_b32_e32 v3, v14
	v_pk_add_f32 v[0:1], v[0:1], v[2:3]
	v_mov_b32_e32 v14, v7
	v_pk_add_f32 v[0:1], v[0:1], v[14:15]
	v_readlane_b32 s72, v254, 10
	v_pk_add_f32 v[0:1], v[0:1], s[0:1] op_sel_hi:[1,0]
	v_readlane_b32 s78, v254, 16
	v_div_scale_f32 v2, s[0:1], v1, v1, 1.0
	v_rcp_f32_e32 v3, v2
	v_readlane_b32 s79, v254, 17
	v_readlane_b32 s4, v254, 41
	v_readlane_b32 s5, v254, 42
	v_fma_f32 v4, -v2, v3, 1.0
	v_fmac_f32_e32 v3, v4, v3
	v_div_scale_f32 v4, vcc, 1.0, v1, 1.0
	v_mul_f32_e32 v5, v4, v3
	v_fma_f32 v6, -v2, v5, v4
	v_fmac_f32_e32 v5, v6, v3
	v_fma_f32 v2, -v2, v5, v4
	v_div_fmas_f32 v2, v2, v3, v5
	v_div_fixup_f32 v1, v2, v1, 1.0
	v_div_scale_f32 v2, s[0:1], v0, v0, 1.0
	v_rcp_f32_e32 v3, v2
	s_lshl_b64 s[0:1], s[62:63], 2
	s_add_u32 s0, s78, s0
	s_addc_u32 s1, s79, s1
	v_fma_f32 v4, -v2, v3, 1.0
	v_fmac_f32_e32 v3, v4, v3
	v_div_scale_f32 v4, vcc, 1.0, v0, 1.0
	v_mul_f32_e32 v5, v4, v3
	v_fma_f32 v6, -v2, v5, v4
	v_fmac_f32_e32 v5, v6, v3
	v_fma_f32 v2, -v2, v5, v4
	v_div_fmas_f32 v2, v2, v3, v5
	v_div_fixup_f32 v0, v2, v0, 1.0
	global_load_dword v2, v112, s[0:1]
	s_lshl_b64 s[0:1], s[62:63], 10
	s_add_u32 s62, s4, s0
	s_addc_u32 s63, s5, s1
	s_lshl_b32 s0, s64, 8
	s_mov_b32 s1, s96
	s_lshl_b64 s[0:1], s[0:1], 2
	s_add_u32 s64, s4, s0
	s_addc_u32 s65, s5, s1
	v_mov_b32_e32 v3, 0
	v_mov_b32_e32 v4, 0
	v_readlane_b32 s73, v254, 11
	v_readlane_b32 s74, v254, 12
	v_readlane_b32 s75, v254, 13
	v_readlane_b32 s76, v254, 14
	v_readlane_b32 s77, v254, 15
	v_readlane_b32 s80, v254, 18
	v_readlane_b32 s81, v254, 19
	v_readlane_b32 s82, v254, 20
	v_readlane_b32 s83, v254, 21
	v_readlane_b32 s84, v254, 22
	v_readlane_b32 s85, v254, 23
	v_readlane_b32 s86, v254, 24
	v_readlane_b32 s87, v254, 25
	s_sub_u32 s0, s64, s62
	v_and_b32_e32 v160, 63, v192
	v_lshrrev_b32_e32 v161, 6, v192
	v_lshl_add_u32 v160, v160, 3, v161
	v_sub_u32_e32 v142, 0x100, v160
	v_sub_u32_e32 v161, 0, v142
	v_max_i32_e32 v161, v142, v161
	v_ashrrev_i32_e32 v162, 31, v142
	v_and_b32_e32 v162, s0, v162
	v_lshl_add_u32 v161, v161, 2, v162
	global_load_dword v150, v161, s[62:63]
	v_add_u32_e32 v143, -1, v142
	v_sub_u32_e32 v161, 0, v143
	v_max_i32_e32 v161, v143, v161
	v_ashrrev_i32_e32 v162, 31, v143
	v_and_b32_e32 v162, s0, v162
	v_lshl_add_u32 v161, v161, 2, v162
	global_load_dword v151, v161, s[62:63]
	v_add_u32_e32 v144, -2, v142
	v_sub_u32_e32 v161, 0, v144
	v_max_i32_e32 v161, v144, v161
	v_ashrrev_i32_e32 v162, 31, v144
	v_and_b32_e32 v162, s0, v162
	v_lshl_add_u32 v161, v161, 2, v162
	global_load_dword v152, v161, s[62:63]
	v_add_u32_e32 v145, -3, v142
	v_sub_u32_e32 v161, 0, v145
	v_max_i32_e32 v161, v145, v161
	v_ashrrev_i32_e32 v162, 31, v145
	v_and_b32_e32 v162, s0, v162
	v_lshl_add_u32 v161, v161, 2, v162
	global_load_dword v153, v161, s[62:63]
	v_add_u32_e32 v146, -4, v142
	v_sub_u32_e32 v161, 0, v146
	v_max_i32_e32 v161, v146, v161
	v_ashrrev_i32_e32 v162, 31, v146
	v_and_b32_e32 v162, s0, v162
	v_lshl_add_u32 v161, v161, 2, v162
	global_load_dword v154, v161, s[62:63]
	v_add_u32_e32 v147, -5, v142
	v_sub_u32_e32 v161, 0, v147
	v_max_i32_e32 v161, v147, v161
	v_ashrrev_i32_e32 v162, 31, v147
	v_and_b32_e32 v162, s0, v162
	v_lshl_add_u32 v161, v161, 2, v162
	global_load_dword v155, v161, s[62:63]
	v_add_u32_e32 v148, -6, v142
	v_sub_u32_e32 v161, 0, v148
	v_max_i32_e32 v161, v148, v161
	v_ashrrev_i32_e32 v162, 31, v148
	v_and_b32_e32 v162, s0, v162
	v_lshl_add_u32 v161, v161, 2, v162
	global_load_dword v156, v161, s[62:63]
	v_add_u32_e32 v149, -7, v142
	v_sub_u32_e32 v161, 0, v149
	v_max_i32_e32 v161, v149, v161
	v_ashrrev_i32_e32 v162, 31, v149
	v_and_b32_e32 v162, s0, v162
	v_lshl_add_u32 v161, v161, 2, v162
	global_load_dword v157, v161, s[62:63]
	global_load_dword v158, v112, s[62:63]
	global_load_dword v159, v112, s[64:65]
	s_waitcnt vmcnt(0)
	v_mul_f32_e32 v158, v0, v158
	v_mul_f32_e32 v159, v1, v159
	v_add_f32_e32 v158, v158, v159
	v_add_f32_e32 v158, v2, v158
	v_cmp_lt_i32_e32 vcc, 0, v142
	v_add_u32_e32 v161, 0xff, v142
	s_nop 0
	v_cndmask_b32_e32 v160, v1, v0, vcc
	v_cmp_eq_u32_e32 vcc, 0, v142
	v_mul_f32_e32 v150, v160, v150
	s_nop 0
	v_cndmask_b32_e32 v150, v150, v158, vcc
	v_cmp_gt_u32_e32 vcc, 0x1ff, v161
	s_nop 1
	v_cndmask_b32_e32 v150, 0, v150, vcc
	v_cmp_lt_i32_e32 vcc, 0, v143
	v_add_u32_e32 v161, 0xff, v143
	s_nop 0
	v_cndmask_b32_e32 v160, v1, v0, vcc
	v_cmp_eq_u32_e32 vcc, 0, v143
	v_mul_f32_e32 v151, v160, v151
	s_nop 0
	v_cndmask_b32_e32 v151, v151, v158, vcc
	v_cmp_gt_u32_e32 vcc, 0x1ff, v161
	s_nop 1
	v_cndmask_b32_e32 v151, 0, v151, vcc
	v_cmp_lt_i32_e32 vcc, 0, v144
	v_add_u32_e32 v161, 0xff, v144
	s_nop 0
	v_cndmask_b32_e32 v160, v1, v0, vcc
	v_cmp_eq_u32_e32 vcc, 0, v144
	v_mul_f32_e32 v152, v160, v152
	s_nop 0
	v_cndmask_b32_e32 v152, v152, v158, vcc
	v_cmp_gt_u32_e32 vcc, 0x1ff, v161
	s_nop 1
	v_cndmask_b32_e32 v152, 0, v152, vcc
	v_cmp_lt_i32_e32 vcc, 0, v145
	v_add_u32_e32 v161, 0xff, v145
	s_nop 0
	v_cndmask_b32_e32 v160, v1, v0, vcc
	v_cmp_eq_u32_e32 vcc, 0, v145
	v_mul_f32_e32 v153, v160, v153
	s_nop 0
	v_cndmask_b32_e32 v153, v153, v158, vcc
	v_cmp_gt_u32_e32 vcc, 0x1ff, v161
	s_nop 1
	v_cndmask_b32_e32 v153, 0, v153, vcc
	v_cmp_lt_i32_e32 vcc, 0, v146
	v_add_u32_e32 v161, 0xff, v146
	s_nop 0
	v_cndmask_b32_e32 v160, v1, v0, vcc
	v_cmp_eq_u32_e32 vcc, 0, v146
	v_mul_f32_e32 v154, v160, v154
	s_nop 0
	v_cndmask_b32_e32 v154, v154, v158, vcc
	v_cmp_gt_u32_e32 vcc, 0x1ff, v161
	s_nop 1
	v_cndmask_b32_e32 v154, 0, v154, vcc
	v_cmp_lt_i32_e32 vcc, 0, v147
	v_add_u32_e32 v161, 0xff, v147
	s_nop 0
	v_cndmask_b32_e32 v160, v1, v0, vcc
	v_cmp_eq_u32_e32 vcc, 0, v147
	v_mul_f32_e32 v155, v160, v155
	s_nop 0
	v_cndmask_b32_e32 v155, v155, v158, vcc
	v_cmp_gt_u32_e32 vcc, 0x1ff, v161
	s_nop 1
	v_cndmask_b32_e32 v155, 0, v155, vcc
	v_cmp_lt_i32_e32 vcc, 0, v148
	v_add_u32_e32 v161, 0xff, v148
	s_nop 0
	v_cndmask_b32_e32 v160, v1, v0, vcc
	v_cmp_eq_u32_e32 vcc, 0, v148
	v_mul_f32_e32 v156, v160, v156
	s_nop 0
	v_cndmask_b32_e32 v156, v156, v158, vcc
	v_cmp_gt_u32_e32 vcc, 0x1ff, v161
	s_nop 1
	v_cndmask_b32_e32 v156, 0, v156, vcc
	v_cmp_lt_i32_e32 vcc, 0, v149
	v_add_u32_e32 v161, 0xff, v149
	s_nop 0
	v_cndmask_b32_e32 v160, v1, v0, vcc
	v_cmp_eq_u32_e32 vcc, 0, v149
	v_mul_f32_e32 v157, v160, v157
	s_nop 0
	v_cndmask_b32_e32 v157, v157, v158, vcc
	v_cmp_gt_u32_e32 vcc, 0x1ff, v161
	s_nop 1
	v_cndmask_b32_e32 v157, 0, v157, vcc
	v_cvt_pk_bf16_f32 v0, v150, v151
	v_cvt_pk_bf16_f32 v1, v152, v153
	v_cvt_pk_bf16_f32 v2, v154, v155
	v_cvt_pk_bf16_f32 v3, v156, v157
	s_and_b64 vcc, exec, s[60:61]
	ds_write_b128 v73, v[0:3]
	s_cbranch_vccz .LBB0_559
	global_load_dwordx4 v[0:3], v[52:53], off
	global_load_dwordx4 v[4:7], v[54:55], off
	v_add_u32_e32 v8, v17, v67
	v_add_u32_e32 v9, v17, v64
	s_waitcnt vmcnt(1)
	ds_write_b128 v8, v[0:3] offset:8320
	s_waitcnt vmcnt(0)
	ds_write_b128 v9, v[4:7] offset:8320
.LBB0_559:
	s_and_b64 s[0:1], exec, s[60:61]
	s_cselect_b32 s0, s90, s70
	s_lshl_b32 s0, s0, 1
	s_mov_b32 s1, s96
	v_lshl_add_u64 v[160:161], v[56:57], 0, s[0:1]
	global_load_dwordx2 v[246:247], v[160:161], off
	global_load_dwordx2 v[248:249], v[160:161], off offset:16
	global_load_dwordx2 v[250:251], v[160:161], off offset:32
	global_load_dwordx2 v[158:159], v[160:161], off offset:48
	v_mov_b32_e32 v0, 0
	s_xor_b64 s[62:63], s[60:61], -1
	v_mov_b32_e32 v1, v0
	v_mov_b32_e32 v2, v0
	v_mov_b32_e32 v3, v0
	v_mov_b32_e32 v4, v0
	v_mov_b32_e32 v5, v0
	v_mov_b32_e32 v6, v0
	v_mov_b32_e32 v7, v0
	v_mov_b32_e32 v8, v0
	v_mov_b32_e32 v9, v0
	v_mov_b32_e32 v10, v0
	v_mov_b32_e32 v11, v0
	v_mov_b32_e32 v12, v0
	v_mov_b32_e32 v13, v0
	v_mov_b32_e32 v14, v0
	v_mov_b32_e32 v15, v0
	s_waitcnt lgkmcnt(0)
	s_barrier
.LBB0_560:
	ds_read_b128 v[214:217], v69 offset:512
	ds_read_b128 v[230:233], v70
	ds_read_b128 v[218:221], v69 offset:544
	ds_read_b128 v[234:237], v70 offset:32
	ds_read_b128 v[222:225], v69 offset:576
	ds_read_b128 v[238:241], v70 offset:64
	ds_read_b128 v[226:229], v69 offset:608
	ds_read_b128 v[242:245], v70 offset:96
	ds_read_b128 v[170:173], v69 offset:640
	ds_read_b128 v[142:145], v70 offset:128
	ds_read_b128 v[174:177], v69 offset:672
	ds_read_b128 v[146:149], v70 offset:160
	ds_read_b128 v[178:181], v69 offset:704
	ds_read_b128 v[150:153], v70 offset:192
	ds_read_b128 v[182:185], v69 offset:736
	ds_read_b128 v[154:157], v70 offset:224
	s_waitcnt lgkmcnt(8)
	v_mfma_f32_32x32x16_bf16 v[0:15], v[214:217], v[230:233], v[0:15]
	v_mfma_f32_32x32x16_bf16 v[0:15], v[218:221], v[234:237], v[0:15]
	v_mfma_f32_32x32x16_bf16 v[0:15], v[222:225], v[238:241], v[0:15]
	v_mfma_f32_32x32x16_bf16 v[0:15], v[226:229], v[242:245], v[0:15]
	ds_read_b128 v[214:217], v69 offset:768
	ds_read_b128 v[230:233], v70 offset:256
	ds_read_b128 v[218:221], v69 offset:800
	ds_read_b128 v[234:237], v70 offset:288
	ds_read_b128 v[222:225], v69 offset:832
	ds_read_b128 v[238:241], v70 offset:320
	ds_read_b128 v[226:229], v69 offset:864
	ds_read_b128 v[242:245], v70 offset:352
	s_waitcnt lgkmcnt(8)
	v_mfma_f32_32x32x16_bf16 v[0:15], v[170:173], v[142:145], v[0:15]
	v_mfma_f32_32x32x16_bf16 v[0:15], v[174:177], v[146:149], v[0:15]
	v_mfma_f32_32x32x16_bf16 v[0:15], v[178:181], v[150:153], v[0:15]
	v_mfma_f32_32x32x16_bf16 v[0:15], v[182:185], v[154:157], v[0:15]
	ds_read_b128 v[170:173], v69 offset:896
	ds_read_b128 v[142:145], v70 offset:384
	ds_read_b128 v[174:177], v69 offset:928
	ds_read_b128 v[146:149], v70 offset:416
	ds_read_b128 v[178:181], v69 offset:960
	ds_read_b128 v[150:153], v70 offset:448
	ds_read_b128 v[182:185], v69 offset:992
	ds_read_b128 v[154:157], v70 offset:480
	s_waitcnt lgkmcnt(8)
	v_mfma_f32_32x32x16_bf16 v[0:15], v[214:217], v[230:233], v[0:15]
	v_mfma_f32_32x32x16_bf16 v[0:15], v[218:221], v[234:237], v[0:15]
	v_mfma_f32_32x32x16_bf16 v[0:15], v[222:225], v[238:241], v[0:15]
	v_mfma_f32_32x32x16_bf16 v[0:15], v[226:229], v[242:245], v[0:15]
	s_waitcnt lgkmcnt(0)
	v_mfma_f32_32x32x16_bf16 v[0:15], v[170:173], v[142:145], v[0:15]
	v_mfma_f32_32x32x16_bf16 v[0:15], v[174:177], v[146:149], v[0:15]
	v_mfma_f32_32x32x16_bf16 v[0:15], v[178:181], v[150:153], v[0:15]
	v_mfma_f32_32x32x16_bf16 v[0:15], v[182:185], v[154:157], v[0:15]
	s_barrier
	s_movk_i32 s0, 0x400
	s_mov_b64 s[60:61], 0
	s_and_b64 vcc, exec, s[62:63]
	s_waitcnt vmcnt(0)
	s_nop 2
	v_lshlrev_b32_e32 v78, 16, v246
	v_and_b32_e32 v79, 0xffff0000, v246
	v_lshlrev_b32_e32 v76, 16, v247
	v_and_b32_e32 v77, 0xffff0000, v247
	v_pk_mul_f32 v[0:1], v[0:1], v[78:79]
	v_pk_mul_f32 v[2:3], v[2:3], v[76:77]
	v_cvt_pk_bf16_f32 v0, v0, v1
	v_cvt_pk_bf16_f32 v1, v2, v3
	v_lshlrev_b32_e32 v76, 16, v248
	v_and_b32_e32 v77, 0xffff0000, v248
	v_pk_mul_f32 v[4:5], v[4:5], v[76:77]
	s_nop 0
	v_cvt_pk_bf16_f32 v2, v4, v5
	v_lshlrev_b32_e32 v4, 16, v249
	v_and_b32_e32 v5, 0xffff0000, v249
	v_pk_mul_f32 v[4:5], v[6:7], v[4:5]
	v_add_u32_e32 v6, 0x2000, v68
	v_cvt_pk_bf16_f32 v3, v4, v5
	ds_write2_b64 v6, v[0:1], v[2:3] offset0:16 offset1:18
	v_lshlrev_b32_e32 v2, 16, v250
	v_and_b32_e32 v3, 0xffff0000, v250
	v_pk_mul_f32 v[2:3], v[8:9], v[2:3]
	s_nop 0
	v_cvt_pk_bf16_f32 v0, v2, v3
	v_lshlrev_b32_e32 v2, 16, v251
	v_and_b32_e32 v3, 0xffff0000, v251
	v_pk_mul_f32 v[2:3], v[10:11], v[2:3]
	s_nop 0
	v_cvt_pk_bf16_f32 v1, v2, v3
	v_lshlrev_b32_e32 v4, 16, v158
	v_and_b32_e32 v5, 0xffff0000, v158
	v_pk_mul_f32 v[4:5], v[12:13], v[4:5]
	s_nop 0
	v_cvt_pk_bf16_f32 v2, v4, v5
	v_lshlrev_b32_e32 v4, 16, v159
	v_and_b32_e32 v5, 0xffff0000, v159
	v_pk_mul_f32 v[4:5], v[14:15], v[4:5]
	s_nop 0
	v_cvt_pk_bf16_f32 v3, v4, v5
	ds_write2_b64 v6, v[0:1], v[2:3] offset0:20 offset1:22
	s_waitcnt lgkmcnt(0)
	s_barrier
	s_cbranch_vccz .LBB0_469
	s_lshl_b32 s0, s90, 1
	v_readlane_b32 s2, v254, 39
	v_readlane_b32 s3, v254, 40
	s_add_u32 s0, s2, s0
	s_addc_u32 s1, s3, 0
	v_lshlrev_b32_e32 v0, 1, v16
	v_mov_b32_e32 v1, v112
	v_lshl_add_u64 v[4:5], s[0:1], 0, v[0:1]
	v_add_u32_e32 v0, v17, v67
	ds_read_b128 v[0:3], v0 offset:8320
	v_lshl_add_u64 v[6:7], v[44:45], 1, v[4:5]
	v_readlane_b32 s8, v255, 7
	v_lshl_add_u64 v[4:5], v[36:37], 1, v[4:5]
	s_mov_b64 s[0:1], 0
	s_waitcnt lgkmcnt(0)
	global_store_dwordx4 v[6:7], v[0:3], off
	s_movk_i32 s74, 0x2400
	s_movk_i32 s64, 0x1fff
	v_add_u32_e32 v0, v17, v64
	ds_read_b128 v[0:3], v0 offset:8320
	v_readlane_b32 s38, v253, 1
	v_readlane_b32 s9, v255, 8
	v_readlane_b32 s39, v253, 2
	s_waitcnt lgkmcnt(0)
	global_store_dwordx4 v[4:5], v[0:3], off
	s_barrier

.Lhy_prio_skip:
.Lhy_s_loop:
	v_add_u32_e32 v161, -1, v161
	v_add_u32_e32 v126, 0xffffff80, v126
	v_cmp_gt_u32_e32 vcc, 64, v161
	v_mad_u32_u24 v162, v161, s83, v65
	s_nop 0
	v_cndmask_b32_e32 v160, v214, v162, vcc
	ds_read_b128 v[216:219], v126
	ds_read_b128 v[232:235], v160
	ds_read_b128 v[220:223], v126 offset:32
	ds_read_b128 v[236:239], v160 offset:32
	ds_read_b128 v[224:227], v126 offset:64
	ds_read_b128 v[240:243], v160 offset:64
	ds_read_b128 v[228:231], v126 offset:96
	ds_read_b128 v[244:247], v160 offset:96
	s_waitcnt lgkmcnt(8)
	v_mfma_f32_32x32x16_bf16 v[0:15], v[142:145], v[170:173], v[0:15]
	v_mfma_f32_32x32x16_bf16 v[0:15], v[146:149], v[174:177], v[0:15]
	v_mfma_f32_32x32x16_bf16 v[0:15], v[150:153], v[178:181], v[0:15]
	v_mfma_f32_32x32x16_bf16 v[0:15], v[154:157], v[182:185], v[0:15]
	v_add_u32_e32 v161, -1, v161
	v_add_u32_e32 v126, 0xffffff80, v126
	v_cmp_gt_u32_e32 vcc, 64, v161
	v_mad_u32_u24 v162, v161, s83, v65
	s_nop 0
	v_cndmask_b32_e32 v127, v214, v162, vcc
	ds_read_b128 v[142:145], v126
	ds_read_b128 v[170:173], v127
	ds_read_b128 v[146:149], v126 offset:32
	ds_read_b128 v[174:177], v127 offset:32
	ds_read_b128 v[150:153], v126 offset:64
	ds_read_b128 v[178:181], v127 offset:64
	ds_read_b128 v[154:157], v126 offset:96
	ds_read_b128 v[182:185], v127 offset:96
	s_waitcnt lgkmcnt(8)
	v_mfma_f32_32x32x16_bf16 v[0:15], v[216:219], v[232:235], v[0:15]
	v_mfma_f32_32x32x16_bf16 v[0:15], v[220:223], v[236:239], v[0:15]
	v_mfma_f32_32x32x16_bf16 v[0:15], v[224:227], v[240:243], v[0:15]
	v_mfma_f32_32x32x16_bf16 v[0:15], v[228:231], v[244:247], v[0:15]
	s_add_i32 s0, s0, -1
	s_cmp_lg_u32 s0, 0
	s_cbranch_scc1 .Lhy_s_loop
	s_and_b64 s[0:1], s[88:89], exec
	s_cselect_b32 s0, s90, s82
	s_lshl_b32 s0, s0, 1
	s_add_u32 s0, s48, s0
	s_addc_u32 s1, s49, 0
	v_lshl_add_u64 v[96:97], v[22:23], 1, s[0:1]
	v_mov_b32_e32 v61, v112
	v_lshl_add_u64 v[96:97], v[96:97], 0, v[60:61]
	v_mov_b32_e32 v63, v112
	v_lshl_add_u64 v[96:97], v[96:97], 0, v[62:63]
	s_mov_b64 s[0:1], 0x4000
	v_lshl_add_u64 v[98:99], v[96:97], 0, s[0:1]
	global_load_dwordx2 v[216:217], v[98:99], off
	global_load_dwordx2 v[218:219], v[98:99], off offset:16
	global_load_dwordx2 v[220:221], v[98:99], off offset:32
	global_load_dwordx2 v[222:223], v[98:99], off offset:48
	s_waitcnt lgkmcnt(0)
	v_mfma_f32_32x32x16_bf16 v[0:15], v[142:145], v[170:173], v[0:15]
	v_mfma_f32_32x32x16_bf16 v[0:15], v[146:149], v[174:177], v[0:15]
	v_mfma_f32_32x32x16_bf16 v[0:15], v[150:153], v[178:181], v[0:15]
	v_mfma_f32_32x32x16_bf16 v[0:15], v[154:157], v[182:185], v[0:15]
	s_setprio 0
	s_barrier
	s_movk_i32 s0, 0x400
	s_mov_b64 s[88:89], 0
	s_and_b64 vcc, exec, s[12:13]
	s_waitcnt vmcnt(0)
	s_nop 1
	v_lshlrev_b32_e32 v100, 16, v216
	v_and_b32_e32 v101, 0xffff0000, v216
	v_lshlrev_b32_e32 v96, 16, v217
	v_and_b32_e32 v97, 0xffff0000, v217
	v_pk_mul_f32 v[0:1], v[0:1], v[100:101]
	v_pk_mul_f32 v[2:3], v[2:3], v[96:97]
	v_cvt_pk_bf16_f32 v0, v0, v1
	v_cvt_pk_bf16_f32 v1, v2, v3
	v_lshlrev_b32_e32 v96, 16, v218
	v_and_b32_e32 v97, 0xffff0000, v218
	v_pk_mul_f32 v[4:5], v[4:5], v[96:97]
	s_nop 0
	v_cvt_pk_bf16_f32 v2, v4, v5
	v_lshlrev_b32_e32 v4, 16, v219
	v_and_b32_e32 v5, 0xffff0000, v219
	v_pk_mul_f32 v[4:5], v[6:7], v[4:5]
	s_nop 0
	v_cvt_pk_bf16_f32 v3, v4, v5
	ds_write2_b64 v76, v[0:1], v[2:3] offset1:2
	v_lshlrev_b32_e32 v2, 16, v220
	v_and_b32_e32 v3, 0xffff0000, v220
	v_pk_mul_f32 v[2:3], v[8:9], v[2:3]
	s_nop 0
	v_cvt_pk_bf16_f32 v0, v2, v3
	v_lshlrev_b32_e32 v2, 16, v221
	v_and_b32_e32 v3, 0xffff0000, v221
	v_pk_mul_f32 v[2:3], v[10:11], v[2:3]
	s_nop 0
	v_cvt_pk_bf16_f32 v1, v2, v3
	v_lshlrev_b32_e32 v4, 16, v222
	v_and_b32_e32 v5, 0xffff0000, v222
	v_pk_mul_f32 v[4:5], v[12:13], v[4:5]
	s_nop 0
	v_cvt_pk_bf16_f32 v2, v4, v5
	v_lshlrev_b32_e32 v4, 16, v223
	v_and_b32_e32 v5, 0xffff0000, v223
	v_pk_mul_f32 v[4:5], v[14:15], v[4:5]
	s_nop 0
	v_cvt_pk_bf16_f32 v3, v4, v5
	ds_write2_b64 v76, v[0:1], v[2:3] offset0:4 offset1:6
	s_waitcnt lgkmcnt(0)
	s_barrier
	s_cbranch_vccz .LBB0_565
	s_lshl_b32 s0, s90, 1
	v_readlane_b32 s2, v254, 39
	v_readlane_b32 s3, v254, 40
	s_add_u32 s0, s2, s0
	s_addc_u32 s1, s3, 0
	v_lshlrev_b32_e32 v0, 1, v16
	v_mov_b32_e32 v1, v112
	v_lshl_add_u64 v[0:1], s[0:1], 0, v[0:1]
	s_mov_b64 s[0:1], 0x4000
	v_lshl_add_u64 v[4:5], v[0:1], 0, s[0:1]
	v_add_u32_e32 v0, v17, v67
	ds_read_b128 v[0:3], v0
	v_lshl_add_u64 v[6:7], v[50:51], 1, v[4:5]
	s_mov_b32 s96, 0
	s_movk_i32 s71, 0x90
	v_lshl_add_u64 v[4:5], v[42:43], 1, v[4:5]
	s_waitcnt lgkmcnt(0)
	global_store_dwordx4 v[6:7], v[0:3], off
	v_readlane_b32 s88, v255, 25
	s_movk_i32 s97, 0x5eed
	v_add_u32_e32 v0, v17, v66
	ds_read_b128 v[0:3], v0
	v_readlane_b32 s38, v253, 1
	s_movk_i32 s74, 0x2400
	s_movk_i32 s64, 0x1fff
	v_readlane_b32 s89, v255, 26
	s_waitcnt lgkmcnt(0)
	global_store_dwordx4 v[4:5], v[0:3], off
	s_barrier
	v_readlane_b32 s39, v253, 2
	s_branch .LBB0_466
